# SSD state pass with batched loads two batches ahead; recurrence value kept in its own register so a later batch load cannot overwrite it
# speedup vs baseline: 1.0092x; 1.0092x over previous
.LBB0_729:
	v_lshlrev_b32_e32 v2, 1, v8
	v_ashrrev_i32_e32 v6, 15, v8
	v_and_b32_e32 v4, 0xc000, v2
	v_and_b32_e32 v2, 0x1fff, v9
	v_lshlrev_b32_e32 v3, 2, v8
	v_ashrrev_i32_e32 v7, 31, v6
	v_lshlrev_b32_e32 v5, 1, v2
	v_and_b32_e32 v12, 0x18000, v3
	v_lshlrev_b32_e32 v13, 2, v2
	v_lshlrev_b64 v[2:3], 22, v[6:7]
	v_lshrrev_b32_e32 v10, 11, v8
	v_or3_b32 v2, v2, v4, v5
	v_lshlrev_b64 v[4:5], 10, v[6:7]
	v_lshlrev_b64 v[6:7], 23, v[6:7]
	v_and_or_b32 v4, v10, 12, v4
	v_or3_b32 v6, v6, v12, v13
	v_mov_b32_e32 v12, 0
	s_mov_b32 s2, -8
	s_waitcnt lgkmcnt(0)
	v_mov_b32_e32 v82, 0x20000
	v_mov_b32_e32 v83, 0
	v_mov_b32_e32 v84, 0x10000
	v_mov_b32_e32 v85, 0
	v_lshl_add_u64 v[74:75], s[8:9], 0, v[6:7]
	v_add_co_u32_e32 v74, vcc, 0x16100000, v74
	s_nop 1
	v_addc_co_u32_e32 v75, vcc, 0, v75, vcc
	v_lshl_add_u64 v[76:77], s[8:9], 0, v[4:5]
	v_add_co_u32_e32 v76, vcc, 0xc0000, v76
	s_nop 1
	v_addc_co_u32_e32 v77, vcc, 0, v77, vcc
	v_lshl_add_u64 v[78:79], s[8:9], 0, v[2:3]
	v_add_co_u32_e32 v78, vcc, 0x17100000, v78
	s_nop 1
	v_addc_co_u32_e32 v79, vcc, 0, v79, vcc
	global_load_dword v26, v[74:75], off
	v_lshl_add_u64 v[74:75], v[74:75], 0, v[82:83]
	global_load_dword v50, v[76:77], off
	global_load_dword v27, v[74:75], off
	v_lshl_add_u64 v[74:75], v[74:75], 0, v[82:83]
	global_load_dword v51, v[76:77], off offset:16
	global_load_dword v28, v[74:75], off
	v_lshl_add_u64 v[74:75], v[74:75], 0, v[82:83]
	global_load_dword v52, v[76:77], off offset:32
	global_load_dword v29, v[74:75], off
	v_lshl_add_u64 v[74:75], v[74:75], 0, v[82:83]
	global_load_dword v53, v[76:77], off offset:48
	global_load_dword v30, v[74:75], off
	v_lshl_add_u64 v[74:75], v[74:75], 0, v[82:83]
	global_load_dword v54, v[76:77], off offset:64
	global_load_dword v31, v[74:75], off
	v_lshl_add_u64 v[74:75], v[74:75], 0, v[82:83]
	global_load_dword v55, v[76:77], off offset:80
	global_load_dword v32, v[74:75], off
	v_lshl_add_u64 v[74:75], v[74:75], 0, v[82:83]
	global_load_dword v56, v[76:77], off offset:96
	global_load_dword v33, v[74:75], off
	v_lshl_add_u64 v[74:75], v[74:75], 0, v[82:83]
	global_load_dword v57, v[76:77], off offset:112
	global_load_dword v34, v[74:75], off
	v_lshl_add_u64 v[74:75], v[74:75], 0, v[82:83]
	global_load_dword v58, v[76:77], off offset:128
	global_load_dword v35, v[74:75], off
	v_lshl_add_u64 v[74:75], v[74:75], 0, v[82:83]
	global_load_dword v59, v[76:77], off offset:144
	global_load_dword v36, v[74:75], off
	v_lshl_add_u64 v[74:75], v[74:75], 0, v[82:83]
	global_load_dword v60, v[76:77], off offset:160
	global_load_dword v37, v[74:75], off
	v_lshl_add_u64 v[74:75], v[74:75], 0, v[82:83]
	global_load_dword v61, v[76:77], off offset:176
	global_load_dword v38, v[74:75], off
	v_lshl_add_u64 v[74:75], v[74:75], 0, v[82:83]
	global_load_dword v62, v[76:77], off offset:192
	global_load_dword v39, v[74:75], off
	v_lshl_add_u64 v[74:75], v[74:75], 0, v[82:83]
	global_load_dword v63, v[76:77], off offset:208
	global_load_dword v40, v[74:75], off
	v_lshl_add_u64 v[74:75], v[74:75], 0, v[82:83]
	global_load_dword v64, v[76:77], off offset:224
	global_load_dword v41, v[74:75], off
	v_lshl_add_u64 v[74:75], v[74:75], 0, v[82:83]
	global_load_dword v65, v[76:77], off offset:240
	global_load_dword v42, v[74:75], off
	v_lshl_add_u64 v[74:75], v[74:75], 0, v[82:83]
	global_load_dword v66, v[76:77], off offset:256
	global_load_dword v43, v[74:75], off
	v_lshl_add_u64 v[74:75], v[74:75], 0, v[82:83]
	global_load_dword v67, v[76:77], off offset:272
	global_load_dword v44, v[74:75], off
	v_lshl_add_u64 v[74:75], v[74:75], 0, v[82:83]
	global_load_dword v68, v[76:77], off offset:288
	global_load_dword v45, v[74:75], off
	v_lshl_add_u64 v[74:75], v[74:75], 0, v[82:83]
	global_load_dword v69, v[76:77], off offset:304
	global_load_dword v46, v[74:75], off
	v_lshl_add_u64 v[74:75], v[74:75], 0, v[82:83]
	global_load_dword v70, v[76:77], off offset:320
	global_load_dword v47, v[74:75], off
	v_lshl_add_u64 v[74:75], v[74:75], 0, v[82:83]
	global_load_dword v71, v[76:77], off offset:336
	global_load_dword v48, v[74:75], off
	v_lshl_add_u64 v[74:75], v[74:75], 0, v[82:83]
	global_load_dword v72, v[76:77], off offset:352
	global_load_dword v49, v[74:75], off
	v_lshl_add_u64 v[74:75], v[74:75], 0, v[82:83]
	global_load_dword v73, v[76:77], off offset:368
	s_waitcnt vmcnt(32)
	v_cvt_pk_bf16_f32 v80, v12, v11
	v_mul_f32_e32 v81, 0x3fb8aa3b, v50
	global_store_short v[78:79], v80, off
	v_exp_f32_e32 v81, v81
	v_lshl_add_u64 v[78:79], v[78:79], 0, v[84:85]
	v_fmac_f32_e32 v26, v12, v81
	v_cvt_pk_bf16_f32 v80, v26, v11
	v_mul_f32_e32 v81, 0x3fb8aa3b, v51
	global_store_short v[78:79], v80, off
	v_exp_f32_e32 v81, v81
	v_lshl_add_u64 v[78:79], v[78:79], 0, v[84:85]
	v_fmac_f32_e32 v27, v26, v81
	v_cvt_pk_bf16_f32 v80, v27, v11
	v_mul_f32_e32 v81, 0x3fb8aa3b, v52
	global_store_short v[78:79], v80, off
	v_exp_f32_e32 v81, v81
	v_lshl_add_u64 v[78:79], v[78:79], 0, v[84:85]
	v_fmac_f32_e32 v28, v27, v81
	v_cvt_pk_bf16_f32 v80, v28, v11
	v_mul_f32_e32 v81, 0x3fb8aa3b, v53
	global_store_short v[78:79], v80, off
	v_exp_f32_e32 v81, v81
	v_lshl_add_u64 v[78:79], v[78:79], 0, v[84:85]
	v_fmac_f32_e32 v29, v28, v81
	v_cvt_pk_bf16_f32 v80, v29, v11
	v_mul_f32_e32 v81, 0x3fb8aa3b, v54
	global_store_short v[78:79], v80, off
	v_exp_f32_e32 v81, v81
	v_lshl_add_u64 v[78:79], v[78:79], 0, v[84:85]
	v_fmac_f32_e32 v30, v29, v81
	v_cvt_pk_bf16_f32 v80, v30, v11
	v_mul_f32_e32 v81, 0x3fb8aa3b, v55
	global_store_short v[78:79], v80, off
	v_exp_f32_e32 v81, v81
	v_lshl_add_u64 v[78:79], v[78:79], 0, v[84:85]
	v_fmac_f32_e32 v31, v30, v81
	v_cvt_pk_bf16_f32 v80, v31, v11
	v_mul_f32_e32 v81, 0x3fb8aa3b, v56
	global_store_short v[78:79], v80, off
	v_exp_f32_e32 v81, v81
	v_lshl_add_u64 v[78:79], v[78:79], 0, v[84:85]
	v_fmac_f32_e32 v32, v31, v81
	v_cvt_pk_bf16_f32 v80, v32, v11
	v_mul_f32_e32 v81, 0x3fb8aa3b, v57
	global_store_short v[78:79], v80, off
	v_exp_f32_e32 v81, v81
	v_lshl_add_u64 v[78:79], v[78:79], 0, v[84:85]
	v_fmac_f32_e32 v33, v32, v81
	v_mov_b32_e32 v12, v33
	global_load_dword v26, v[74:75], off
	v_lshl_add_u64 v[74:75], v[74:75], 0, v[82:83]
	global_load_dword v50, v[76:77], off offset:384
	global_load_dword v27, v[74:75], off
	v_lshl_add_u64 v[74:75], v[74:75], 0, v[82:83]
	global_load_dword v51, v[76:77], off offset:400
	global_load_dword v28, v[74:75], off
	v_lshl_add_u64 v[74:75], v[74:75], 0, v[82:83]
	global_load_dword v52, v[76:77], off offset:416
	global_load_dword v29, v[74:75], off
	v_lshl_add_u64 v[74:75], v[74:75], 0, v[82:83]
	global_load_dword v53, v[76:77], off offset:432
	global_load_dword v30, v[74:75], off
	v_lshl_add_u64 v[74:75], v[74:75], 0, v[82:83]
	global_load_dword v54, v[76:77], off offset:448
	global_load_dword v31, v[74:75], off
	v_lshl_add_u64 v[74:75], v[74:75], 0, v[82:83]
	global_load_dword v55, v[76:77], off offset:464
	global_load_dword v32, v[74:75], off
	v_lshl_add_u64 v[74:75], v[74:75], 0, v[82:83]
	global_load_dword v56, v[76:77], off offset:480
	global_load_dword v33, v[74:75], off
	v_lshl_add_u64 v[74:75], v[74:75], 0, v[82:83]
	global_load_dword v57, v[76:77], off offset:496
	s_waitcnt vmcnt(40)
	v_cvt_pk_bf16_f32 v80, v12, v11
	v_mul_f32_e32 v81, 0x3fb8aa3b, v58
	global_store_short v[78:79], v80, off
	v_exp_f32_e32 v81, v81
	v_lshl_add_u64 v[78:79], v[78:79], 0, v[84:85]
	v_fmac_f32_e32 v34, v12, v81
	v_cvt_pk_bf16_f32 v80, v34, v11
	v_mul_f32_e32 v81, 0x3fb8aa3b, v59
	global_store_short v[78:79], v80, off
	v_exp_f32_e32 v81, v81
	v_lshl_add_u64 v[78:79], v[78:79], 0, v[84:85]
	v_fmac_f32_e32 v35, v34, v81
	v_cvt_pk_bf16_f32 v80, v35, v11
	v_mul_f32_e32 v81, 0x3fb8aa3b, v60
	global_store_short v[78:79], v80, off
	v_exp_f32_e32 v81, v81
	v_lshl_add_u64 v[78:79], v[78:79], 0, v[84:85]
	v_fmac_f32_e32 v36, v35, v81
	v_cvt_pk_bf16_f32 v80, v36, v11
	v_mul_f32_e32 v81, 0x3fb8aa3b, v61
	global_store_short v[78:79], v80, off
	v_exp_f32_e32 v81, v81
	v_lshl_add_u64 v[78:79], v[78:79], 0, v[84:85]
	v_fmac_f32_e32 v37, v36, v81
	v_cvt_pk_bf16_f32 v80, v37, v11
	v_mul_f32_e32 v81, 0x3fb8aa3b, v62
	global_store_short v[78:79], v80, off
	v_exp_f32_e32 v81, v81
	v_lshl_add_u64 v[78:79], v[78:79], 0, v[84:85]
	v_fmac_f32_e32 v38, v37, v81
	v_cvt_pk_bf16_f32 v80, v38, v11
	v_mul_f32_e32 v81, 0x3fb8aa3b, v63
	global_store_short v[78:79], v80, off
	v_exp_f32_e32 v81, v81
	v_lshl_add_u64 v[78:79], v[78:79], 0, v[84:85]
	v_fmac_f32_e32 v39, v38, v81
	v_cvt_pk_bf16_f32 v80, v39, v11
	v_mul_f32_e32 v81, 0x3fb8aa3b, v64
	global_store_short v[78:79], v80, off
	v_exp_f32_e32 v81, v81
	v_lshl_add_u64 v[78:79], v[78:79], 0, v[84:85]
	v_fmac_f32_e32 v40, v39, v81
	v_cvt_pk_bf16_f32 v80, v40, v11
	v_mul_f32_e32 v81, 0x3fb8aa3b, v65
	global_store_short v[78:79], v80, off
	v_exp_f32_e32 v81, v81
	v_lshl_add_u64 v[78:79], v[78:79], 0, v[84:85]
	v_fmac_f32_e32 v41, v40, v81
	v_mov_b32_e32 v12, v41
	global_load_dword v34, v[74:75], off
	v_lshl_add_u64 v[74:75], v[74:75], 0, v[82:83]
	global_load_dword v58, v[76:77], off offset:512
	global_load_dword v35, v[74:75], off
	v_lshl_add_u64 v[74:75], v[74:75], 0, v[82:83]
	global_load_dword v59, v[76:77], off offset:528
	global_load_dword v36, v[74:75], off
	v_lshl_add_u64 v[74:75], v[74:75], 0, v[82:83]
	global_load_dword v60, v[76:77], off offset:544
	global_load_dword v37, v[74:75], off
	v_lshl_add_u64 v[74:75], v[74:75], 0, v[82:83]
	global_load_dword v61, v[76:77], off offset:560
	global_load_dword v38, v[74:75], off
	v_lshl_add_u64 v[74:75], v[74:75], 0, v[82:83]
	global_load_dword v62, v[76:77], off offset:576
	global_load_dword v39, v[74:75], off
	v_lshl_add_u64 v[74:75], v[74:75], 0, v[82:83]
	global_load_dword v63, v[76:77], off offset:592
	global_load_dword v40, v[74:75], off
	v_lshl_add_u64 v[74:75], v[74:75], 0, v[82:83]
	global_load_dword v64, v[76:77], off offset:608
	global_load_dword v41, v[74:75], off
	v_lshl_add_u64 v[74:75], v[74:75], 0, v[82:83]
	global_load_dword v65, v[76:77], off offset:624
	s_waitcnt vmcnt(40)
	v_cvt_pk_bf16_f32 v80, v12, v11
	v_mul_f32_e32 v81, 0x3fb8aa3b, v66
	global_store_short v[78:79], v80, off
	v_exp_f32_e32 v81, v81
	v_lshl_add_u64 v[78:79], v[78:79], 0, v[84:85]
	v_fmac_f32_e32 v42, v12, v81
	v_cvt_pk_bf16_f32 v80, v42, v11
	v_mul_f32_e32 v81, 0x3fb8aa3b, v67
	global_store_short v[78:79], v80, off
	v_exp_f32_e32 v81, v81
	v_lshl_add_u64 v[78:79], v[78:79], 0, v[84:85]
	v_fmac_f32_e32 v43, v42, v81
	v_cvt_pk_bf16_f32 v80, v43, v11
	v_mul_f32_e32 v81, 0x3fb8aa3b, v68
	global_store_short v[78:79], v80, off
	v_exp_f32_e32 v81, v81
	v_lshl_add_u64 v[78:79], v[78:79], 0, v[84:85]
	v_fmac_f32_e32 v44, v43, v81
	v_cvt_pk_bf16_f32 v80, v44, v11
	v_mul_f32_e32 v81, 0x3fb8aa3b, v69
	global_store_short v[78:79], v80, off
	v_exp_f32_e32 v81, v81
	v_lshl_add_u64 v[78:79], v[78:79], 0, v[84:85]
	v_fmac_f32_e32 v45, v44, v81
	v_cvt_pk_bf16_f32 v80, v45, v11
	v_mul_f32_e32 v81, 0x3fb8aa3b, v70
	global_store_short v[78:79], v80, off
	v_exp_f32_e32 v81, v81
	v_lshl_add_u64 v[78:79], v[78:79], 0, v[84:85]
	v_fmac_f32_e32 v46, v45, v81
	v_cvt_pk_bf16_f32 v80, v46, v11
	v_mul_f32_e32 v81, 0x3fb8aa3b, v71
	global_store_short v[78:79], v80, off
	v_exp_f32_e32 v81, v81
	v_lshl_add_u64 v[78:79], v[78:79], 0, v[84:85]
	v_fmac_f32_e32 v47, v46, v81
	v_cvt_pk_bf16_f32 v80, v47, v11
	v_mul_f32_e32 v81, 0x3fb8aa3b, v72
	global_store_short v[78:79], v80, off
	v_exp_f32_e32 v81, v81
	v_lshl_add_u64 v[78:79], v[78:79], 0, v[84:85]
	v_fmac_f32_e32 v48, v47, v81
	v_cvt_pk_bf16_f32 v80, v48, v11
	v_mul_f32_e32 v81, 0x3fb8aa3b, v73
	global_store_short v[78:79], v80, off
	v_exp_f32_e32 v81, v81
	v_lshl_add_u64 v[78:79], v[78:79], 0, v[84:85]
	v_fmac_f32_e32 v49, v48, v81
	v_mov_b32_e32 v12, v49
	global_load_dword v42, v[74:75], off
	v_lshl_add_u64 v[74:75], v[74:75], 0, v[82:83]
	global_load_dword v66, v[76:77], off offset:640
	global_load_dword v43, v[74:75], off
	v_lshl_add_u64 v[74:75], v[74:75], 0, v[82:83]
	global_load_dword v67, v[76:77], off offset:656
	global_load_dword v44, v[74:75], off
	v_lshl_add_u64 v[74:75], v[74:75], 0, v[82:83]
	global_load_dword v68, v[76:77], off offset:672
	global_load_dword v45, v[74:75], off
	v_lshl_add_u64 v[74:75], v[74:75], 0, v[82:83]
	global_load_dword v69, v[76:77], off offset:688
	global_load_dword v46, v[74:75], off
	v_lshl_add_u64 v[74:75], v[74:75], 0, v[82:83]
	global_load_dword v70, v[76:77], off offset:704
	global_load_dword v47, v[74:75], off
	v_lshl_add_u64 v[74:75], v[74:75], 0, v[82:83]
	global_load_dword v71, v[76:77], off offset:720
	global_load_dword v48, v[74:75], off
	v_lshl_add_u64 v[74:75], v[74:75], 0, v[82:83]
	global_load_dword v72, v[76:77], off offset:736
	global_load_dword v49, v[74:75], off
	v_lshl_add_u64 v[74:75], v[74:75], 0, v[82:83]
	global_load_dword v73, v[76:77], off offset:752
	s_waitcnt vmcnt(40)
	v_cvt_pk_bf16_f32 v80, v12, v11
	v_mul_f32_e32 v81, 0x3fb8aa3b, v50
	global_store_short v[78:79], v80, off
	v_exp_f32_e32 v81, v81
	v_lshl_add_u64 v[78:79], v[78:79], 0, v[84:85]
	v_fmac_f32_e32 v26, v12, v81
	v_cvt_pk_bf16_f32 v80, v26, v11
	v_mul_f32_e32 v81, 0x3fb8aa3b, v51
	global_store_short v[78:79], v80, off
	v_exp_f32_e32 v81, v81
	v_lshl_add_u64 v[78:79], v[78:79], 0, v[84:85]
	v_fmac_f32_e32 v27, v26, v81
	v_cvt_pk_bf16_f32 v80, v27, v11
	v_mul_f32_e32 v81, 0x3fb8aa3b, v52
	global_store_short v[78:79], v80, off
	v_exp_f32_e32 v81, v81
	v_lshl_add_u64 v[78:79], v[78:79], 0, v[84:85]
	v_fmac_f32_e32 v28, v27, v81
	v_cvt_pk_bf16_f32 v80, v28, v11
	v_mul_f32_e32 v81, 0x3fb8aa3b, v53
	global_store_short v[78:79], v80, off
	v_exp_f32_e32 v81, v81
	v_lshl_add_u64 v[78:79], v[78:79], 0, v[84:85]
	v_fmac_f32_e32 v29, v28, v81
	v_cvt_pk_bf16_f32 v80, v29, v11
	v_mul_f32_e32 v81, 0x3fb8aa3b, v54
	global_store_short v[78:79], v80, off
	v_exp_f32_e32 v81, v81
	v_lshl_add_u64 v[78:79], v[78:79], 0, v[84:85]
	v_fmac_f32_e32 v30, v29, v81
	v_cvt_pk_bf16_f32 v80, v30, v11
	v_mul_f32_e32 v81, 0x3fb8aa3b, v55
	global_store_short v[78:79], v80, off
	v_exp_f32_e32 v81, v81
	v_lshl_add_u64 v[78:79], v[78:79], 0, v[84:85]
	v_fmac_f32_e32 v31, v30, v81
	v_cvt_pk_bf16_f32 v80, v31, v11
	v_mul_f32_e32 v81, 0x3fb8aa3b, v56
	global_store_short v[78:79], v80, off
	v_exp_f32_e32 v81, v81
	v_lshl_add_u64 v[78:79], v[78:79], 0, v[84:85]
	v_fmac_f32_e32 v32, v31, v81
	v_cvt_pk_bf16_f32 v80, v32, v11
	v_mul_f32_e32 v81, 0x3fb8aa3b, v57
	global_store_short v[78:79], v80, off
	v_exp_f32_e32 v81, v81
	v_lshl_add_u64 v[78:79], v[78:79], 0, v[84:85]
	v_fmac_f32_e32 v33, v32, v81
	v_mov_b32_e32 v12, v33
	global_load_dword v26, v[74:75], off
	v_lshl_add_u64 v[74:75], v[74:75], 0, v[82:83]
	global_load_dword v50, v[76:77], off offset:768
	global_load_dword v27, v[74:75], off
	v_lshl_add_u64 v[74:75], v[74:75], 0, v[82:83]
	global_load_dword v51, v[76:77], off offset:784
	global_load_dword v28, v[74:75], off
	v_lshl_add_u64 v[74:75], v[74:75], 0, v[82:83]
	global_load_dword v52, v[76:77], off offset:800
	global_load_dword v29, v[74:75], off
	v_lshl_add_u64 v[74:75], v[74:75], 0, v[82:83]
	global_load_dword v53, v[76:77], off offset:816
	global_load_dword v30, v[74:75], off
	v_lshl_add_u64 v[74:75], v[74:75], 0, v[82:83]
	global_load_dword v54, v[76:77], off offset:832
	global_load_dword v31, v[74:75], off
	v_lshl_add_u64 v[74:75], v[74:75], 0, v[82:83]
	global_load_dword v55, v[76:77], off offset:848
	global_load_dword v32, v[74:75], off
	v_lshl_add_u64 v[74:75], v[74:75], 0, v[82:83]
	global_load_dword v56, v[76:77], off offset:864
	global_load_dword v33, v[74:75], off
	v_lshl_add_u64 v[74:75], v[74:75], 0, v[82:83]
	global_load_dword v57, v[76:77], off offset:880
	s_waitcnt vmcnt(40)
	v_cvt_pk_bf16_f32 v80, v12, v11
	v_mul_f32_e32 v81, 0x3fb8aa3b, v58
	global_store_short v[78:79], v80, off
	v_exp_f32_e32 v81, v81
	v_lshl_add_u64 v[78:79], v[78:79], 0, v[84:85]
	v_fmac_f32_e32 v34, v12, v81
	v_cvt_pk_bf16_f32 v80, v34, v11
	v_mul_f32_e32 v81, 0x3fb8aa3b, v59
	global_store_short v[78:79], v80, off
	v_exp_f32_e32 v81, v81
	v_lshl_add_u64 v[78:79], v[78:79], 0, v[84:85]
	v_fmac_f32_e32 v35, v34, v81
	v_cvt_pk_bf16_f32 v80, v35, v11
	v_mul_f32_e32 v81, 0x3fb8aa3b, v60
	global_store_short v[78:79], v80, off
	v_exp_f32_e32 v81, v81
	v_lshl_add_u64 v[78:79], v[78:79], 0, v[84:85]
	v_fmac_f32_e32 v36, v35, v81
	v_cvt_pk_bf16_f32 v80, v36, v11
	v_mul_f32_e32 v81, 0x3fb8aa3b, v61
	global_store_short v[78:79], v80, off
	v_exp_f32_e32 v81, v81
	v_lshl_add_u64 v[78:79], v[78:79], 0, v[84:85]
	v_fmac_f32_e32 v37, v36, v81
	v_cvt_pk_bf16_f32 v80, v37, v11
	v_mul_f32_e32 v81, 0x3fb8aa3b, v62
	global_store_short v[78:79], v80, off
	v_exp_f32_e32 v81, v81
	v_lshl_add_u64 v[78:79], v[78:79], 0, v[84:85]
	v_fmac_f32_e32 v38, v37, v81
	v_cvt_pk_bf16_f32 v80, v38, v11
	v_mul_f32_e32 v81, 0x3fb8aa3b, v63
	global_store_short v[78:79], v80, off
	v_exp_f32_e32 v81, v81
	v_lshl_add_u64 v[78:79], v[78:79], 0, v[84:85]
	v_fmac_f32_e32 v39, v38, v81
	v_cvt_pk_bf16_f32 v80, v39, v11
	v_mul_f32_e32 v81, 0x3fb8aa3b, v64
	global_store_short v[78:79], v80, off
	v_exp_f32_e32 v81, v81
	v_lshl_add_u64 v[78:79], v[78:79], 0, v[84:85]
	v_fmac_f32_e32 v40, v39, v81
	v_cvt_pk_bf16_f32 v80, v40, v11
	v_mul_f32_e32 v81, 0x3fb8aa3b, v65
	global_store_short v[78:79], v80, off
	v_exp_f32_e32 v81, v81
	v_lshl_add_u64 v[78:79], v[78:79], 0, v[84:85]
	v_fmac_f32_e32 v41, v40, v81
	v_mov_b32_e32 v12, v41
	global_load_dword v34, v[74:75], off
	v_lshl_add_u64 v[74:75], v[74:75], 0, v[82:83]
	global_load_dword v58, v[76:77], off offset:896
	global_load_dword v35, v[74:75], off
	v_lshl_add_u64 v[74:75], v[74:75], 0, v[82:83]
	global_load_dword v59, v[76:77], off offset:912
	global_load_dword v36, v[74:75], off
	v_lshl_add_u64 v[74:75], v[74:75], 0, v[82:83]
	global_load_dword v60, v[76:77], off offset:928
	global_load_dword v37, v[74:75], off
	v_lshl_add_u64 v[74:75], v[74:75], 0, v[82:83]
	global_load_dword v61, v[76:77], off offset:944
	global_load_dword v38, v[74:75], off
	v_lshl_add_u64 v[74:75], v[74:75], 0, v[82:83]
	global_load_dword v62, v[76:77], off offset:960
	global_load_dword v39, v[74:75], off
	v_lshl_add_u64 v[74:75], v[74:75], 0, v[82:83]
	global_load_dword v63, v[76:77], off offset:976
	global_load_dword v40, v[74:75], off
	v_lshl_add_u64 v[74:75], v[74:75], 0, v[82:83]
	global_load_dword v64, v[76:77], off offset:992
	global_load_dword v41, v[74:75], off
	v_lshl_add_u64 v[74:75], v[74:75], 0, v[82:83]
	global_load_dword v65, v[76:77], off offset:1008
	s_waitcnt vmcnt(40)
	v_cvt_pk_bf16_f32 v80, v12, v11
	v_mul_f32_e32 v81, 0x3fb8aa3b, v66
	global_store_short v[78:79], v80, off
	v_exp_f32_e32 v81, v81
	v_lshl_add_u64 v[78:79], v[78:79], 0, v[84:85]
	v_fmac_f32_e32 v42, v12, v81
	v_cvt_pk_bf16_f32 v80, v42, v11
	v_mul_f32_e32 v81, 0x3fb8aa3b, v67
	global_store_short v[78:79], v80, off
	v_exp_f32_e32 v81, v81
	v_lshl_add_u64 v[78:79], v[78:79], 0, v[84:85]
	v_fmac_f32_e32 v43, v42, v81
	v_cvt_pk_bf16_f32 v80, v43, v11
	v_mul_f32_e32 v81, 0x3fb8aa3b, v68
	global_store_short v[78:79], v80, off
	v_exp_f32_e32 v81, v81
	v_lshl_add_u64 v[78:79], v[78:79], 0, v[84:85]
	v_fmac_f32_e32 v44, v43, v81
	v_cvt_pk_bf16_f32 v80, v44, v11
	v_mul_f32_e32 v81, 0x3fb8aa3b, v69
	global_store_short v[78:79], v80, off
	v_exp_f32_e32 v81, v81
	v_lshl_add_u64 v[78:79], v[78:79], 0, v[84:85]
	v_fmac_f32_e32 v45, v44, v81
	v_cvt_pk_bf16_f32 v80, v45, v11
	v_mul_f32_e32 v81, 0x3fb8aa3b, v70
	global_store_short v[78:79], v80, off
	v_exp_f32_e32 v81, v81
	v_lshl_add_u64 v[78:79], v[78:79], 0, v[84:85]
	v_fmac_f32_e32 v46, v45, v81
	v_cvt_pk_bf16_f32 v80, v46, v11
	v_mul_f32_e32 v81, 0x3fb8aa3b, v71
	global_store_short v[78:79], v80, off
	v_exp_f32_e32 v81, v81
	v_lshl_add_u64 v[78:79], v[78:79], 0, v[84:85]
	v_fmac_f32_e32 v47, v46, v81
	v_cvt_pk_bf16_f32 v80, v47, v11
	v_mul_f32_e32 v81, 0x3fb8aa3b, v72
	global_store_short v[78:79], v80, off
	v_exp_f32_e32 v81, v81
	v_lshl_add_u64 v[78:79], v[78:79], 0, v[84:85]
	v_fmac_f32_e32 v48, v47, v81
	v_cvt_pk_bf16_f32 v80, v48, v11
	v_mul_f32_e32 v81, 0x3fb8aa3b, v73
	global_store_short v[78:79], v80, off
	v_exp_f32_e32 v81, v81
	v_lshl_add_u64 v[78:79], v[78:79], 0, v[84:85]
	v_fmac_f32_e32 v49, v48, v81
	v_mov_b32_e32 v12, v49
	s_waitcnt vmcnt(24)
	v_cvt_pk_bf16_f32 v80, v12, v11
	v_mul_f32_e32 v81, 0x3fb8aa3b, v50
	global_store_short v[78:79], v80, off
	v_exp_f32_e32 v81, v81
	v_lshl_add_u64 v[78:79], v[78:79], 0, v[84:85]
	v_fmac_f32_e32 v26, v12, v81
	v_cvt_pk_bf16_f32 v80, v26, v11
	v_mul_f32_e32 v81, 0x3fb8aa3b, v51
	global_store_short v[78:79], v80, off
	v_exp_f32_e32 v81, v81
	v_lshl_add_u64 v[78:79], v[78:79], 0, v[84:85]
	v_fmac_f32_e32 v27, v26, v81
	v_cvt_pk_bf16_f32 v80, v27, v11
	v_mul_f32_e32 v81, 0x3fb8aa3b, v52
	global_store_short v[78:79], v80, off
	v_exp_f32_e32 v81, v81
	v_lshl_add_u64 v[78:79], v[78:79], 0, v[84:85]
	v_fmac_f32_e32 v28, v27, v81
	v_cvt_pk_bf16_f32 v80, v28, v11
	v_mul_f32_e32 v81, 0x3fb8aa3b, v53
	global_store_short v[78:79], v80, off
	v_exp_f32_e32 v81, v81
	v_lshl_add_u64 v[78:79], v[78:79], 0, v[84:85]
	v_fmac_f32_e32 v29, v28, v81
	v_cvt_pk_bf16_f32 v80, v29, v11
	v_mul_f32_e32 v81, 0x3fb8aa3b, v54
	global_store_short v[78:79], v80, off
	v_exp_f32_e32 v81, v81
	v_lshl_add_u64 v[78:79], v[78:79], 0, v[84:85]
	v_fmac_f32_e32 v30, v29, v81
	v_cvt_pk_bf16_f32 v80, v30, v11
	v_mul_f32_e32 v81, 0x3fb8aa3b, v55
	global_store_short v[78:79], v80, off
	v_exp_f32_e32 v81, v81
	v_lshl_add_u64 v[78:79], v[78:79], 0, v[84:85]
	v_fmac_f32_e32 v31, v30, v81
	v_cvt_pk_bf16_f32 v80, v31, v11
	v_mul_f32_e32 v81, 0x3fb8aa3b, v56
	global_store_short v[78:79], v80, off
	v_exp_f32_e32 v81, v81
	v_lshl_add_u64 v[78:79], v[78:79], 0, v[84:85]
	v_fmac_f32_e32 v32, v31, v81
	v_cvt_pk_bf16_f32 v80, v32, v11
	v_mul_f32_e32 v81, 0x3fb8aa3b, v57
	global_store_short v[78:79], v80, off
	v_exp_f32_e32 v81, v81
	v_lshl_add_u64 v[78:79], v[78:79], 0, v[84:85]
	v_fmac_f32_e32 v33, v32, v81
	v_mov_b32_e32 v12, v33
	s_waitcnt vmcnt(8)
	v_cvt_pk_bf16_f32 v80, v12, v11
	v_mul_f32_e32 v81, 0x3fb8aa3b, v58
	global_store_short v[78:79], v80, off
	v_exp_f32_e32 v81, v81
	v_lshl_add_u64 v[78:79], v[78:79], 0, v[84:85]
	v_fmac_f32_e32 v34, v12, v81
	v_cvt_pk_bf16_f32 v80, v34, v11
	v_mul_f32_e32 v81, 0x3fb8aa3b, v59
	global_store_short v[78:79], v80, off
	v_exp_f32_e32 v81, v81
	v_lshl_add_u64 v[78:79], v[78:79], 0, v[84:85]
	v_fmac_f32_e32 v35, v34, v81
	v_cvt_pk_bf16_f32 v80, v35, v11
	v_mul_f32_e32 v81, 0x3fb8aa3b, v60
	global_store_short v[78:79], v80, off
	v_exp_f32_e32 v81, v81
	v_lshl_add_u64 v[78:79], v[78:79], 0, v[84:85]
	v_fmac_f32_e32 v36, v35, v81
	v_cvt_pk_bf16_f32 v80, v36, v11
	v_mul_f32_e32 v81, 0x3fb8aa3b, v61
	global_store_short v[78:79], v80, off
	v_exp_f32_e32 v81, v81
	v_lshl_add_u64 v[78:79], v[78:79], 0, v[84:85]
	v_fmac_f32_e32 v37, v36, v81
	v_cvt_pk_bf16_f32 v80, v37, v11
	v_mul_f32_e32 v81, 0x3fb8aa3b, v62
	global_store_short v[78:79], v80, off
	v_exp_f32_e32 v81, v81
	v_lshl_add_u64 v[78:79], v[78:79], 0, v[84:85]
	v_fmac_f32_e32 v38, v37, v81
	v_cvt_pk_bf16_f32 v80, v38, v11
	v_mul_f32_e32 v81, 0x3fb8aa3b, v63
	global_store_short v[78:79], v80, off
	v_exp_f32_e32 v81, v81
	v_lshl_add_u64 v[78:79], v[78:79], 0, v[84:85]
	v_fmac_f32_e32 v39, v38, v81
	v_cvt_pk_bf16_f32 v80, v39, v11
	v_mul_f32_e32 v81, 0x3fb8aa3b, v64
	global_store_short v[78:79], v80, off
	v_exp_f32_e32 v81, v81
	v_lshl_add_u64 v[78:79], v[78:79], 0, v[84:85]
	v_fmac_f32_e32 v40, v39, v81
	v_cvt_pk_bf16_f32 v80, v40, v11
	v_mul_f32_e32 v81, 0x3fb8aa3b, v65
	global_store_short v[78:79], v80, off
	v_exp_f32_e32 v81, v81
	v_lshl_add_u64 v[78:79], v[78:79], 0, v[84:85]
	v_fmac_f32_e32 v41, v40, v81
	v_mov_b32_e32 v12, v41
	v_mov_b32_e32 v12, v12
	v_readlane_b32 s4, v243, 17
	s_mov_b32 s2, 0xffff
	s_nop 0
	v_add_u32_e32 v8, s4, v8
	v_cmp_lt_i32_e32 vcc, s2, v8
	s_or_b64 s[10:11], vcc, s[10:11]
	v_add_u16_e32 v9, s4, v9
	s_andn2_b64 exec, exec, s[10:11]
	s_cbranch_execnz .LBB0_729
